# MLA loops: cross-half row-max exchange via v_permlane32_swap (no LDS round trip), single accumulation chain for the 12 QK MFMAs
# speedup vs baseline: 1.0133x; 1.0030x over previous
; #define LAS __attribute__((address_space(3)))
; DI int crow(int i, int h) { return (i & 3) + 8 * (i >> 2) + 4 * h; }
; #define MFMA32(a, b, c) __builtin_amdgcn_mfma_f32_32x32x16_bf16((a), (b), (c), 0, 0, 0)
; template <bool ATOM>
; DI void mla_unit(LAS unsigned char* lds, const AttnPtrs& P, int b, int hd, int qb) {
;     ...
;         if (keyb <= qb * 128 + rg * 32 + 31) {
;             const LAS unsigned char* Kw = lds + (t & 1) * BUFB + kwo;
;             const LAS unsigned char* Vw = lds + (t & 1) * BUFB + vwo;
;             f32x16 xa, xb;
; #pragma unroll
;             for (int i = 0; i < 16; ++i) { xa[i] = 0.f; xb[i] = 0.f; }
; #pragma unroll
;             for (int kk = 0; kk < NKK; kk += 2) {
;                 const bf16x8 a0 = *(const LAS bf16x8*)(Kw + kk * 32), a1 = *(const LAS bf16x8*)(Kw + kk * 32 + 32);
;                 xa = MFMA32(a0, qf[kk], xa); xb = MFMA32(a1, qf[kk + 1], xb);
;                 if ((kk & 3) == 2) __builtin_amdgcn_sched_barrier(0);
;             }
;             f32x16 x0;
; #pragma unroll
;             for (int i = 0; i < 16; ++i) x0[i] = xa[i] + xb[i];
;             if (keyb + 31 > qb * 128 + rg * 32) {
; #pragma unroll
;                 for (int i = 0; i < 16; ++i) if (keyb + crow(i, h) > fq_) x0[i] = -INFINITY;
;             }
;             float mloc = x0[0];
; #pragma unroll
;             for (int i = 1; i < 16; ++i) mloc = fmaxf(mloc, x0[i]);
;             mloc = fmaxf(mloc, __shfl_xor(mloc, 32));
.LBB0_1051:
	s_add_i32 s40, s35, s14
	s_cmp_gt_i32 s40, s36
	s_cbranch_scc1 .LBB0_1057
	s_bitcmp1_b32 s4, 0
	s_cselect_b32 s4, 0xac00, 0
	s_add_i32 s4, s4, 0
	v_add3_u32 v125, s4, v215, v128
	ds_read_b128 v[0:3], v125
	ds_read_b128 v[80:83], v125 offset:32
	ds_read_b128 v[216:219], v125 offset:64
	s_waitcnt lgkmcnt(2)
	v_mfma_f32_32x32x16_bf16 v[0:15], v[0:3], v[180:183], 0
	s_waitcnt lgkmcnt(0)
	v_mfma_f32_32x32x16_bf16 v[0:15], v[216:219], v[172:175], v[0:15]
	ds_read_b128 v[216:219], v125 offset:96
	v_mfma_f32_32x32x16_bf16 v[0:15], v[80:83], v[176:179], v[0:15]
	s_waitcnt lgkmcnt(0)
	v_mfma_f32_32x32x16_bf16 v[0:15], v[216:219], v[168:171], v[0:15]
	ds_read_b128 v[216:219], v125 offset:128
	s_waitcnt lgkmcnt(0)
	v_mfma_f32_32x32x16_bf16 v[0:15], v[216:219], v[164:167], v[0:15]
	ds_read_b128 v[216:219], v125 offset:160
	s_waitcnt lgkmcnt(0)
	v_mfma_f32_32x32x16_bf16 v[0:15], v[216:219], v[160:163], v[0:15]
	ds_read_b128 v[216:219], v125 offset:192
	s_waitcnt lgkmcnt(0)
	v_mfma_f32_32x32x16_bf16 v[0:15], v[216:219], v[156:159], v[0:15]
	ds_read_b128 v[216:219], v125 offset:224
	s_waitcnt lgkmcnt(0)
	v_mfma_f32_32x32x16_bf16 v[0:15], v[216:219], v[152:155], v[0:15]
	ds_read_b128 v[216:219], v125 offset:256
	s_waitcnt lgkmcnt(0)
	v_mfma_f32_32x32x16_bf16 v[0:15], v[216:219], v[148:151], v[0:15]
	ds_read_b128 v[216:219], v125 offset:288
	s_waitcnt lgkmcnt(0)
	v_mfma_f32_32x32x16_bf16 v[0:15], v[216:219], v[144:147], v[0:15]
	ds_read_b128 v[216:219], v125 offset:320
	s_waitcnt lgkmcnt(0)
	v_mfma_f32_32x32x16_bf16 v[0:15], v[216:219], v[140:143], v[0:15]
	ds_read_b128 v[216:219], v125 offset:352
	s_waitcnt lgkmcnt(0)
	v_mfma_f32_32x32x16_bf16 v[0:15], v[216:219], v[136:139], v[0:15]
	s_add_i32 s40, s40, 31
	s_nop 10
	v_mov_b32_e32 v80, v0
	v_mov_b32_e32 v81, v1
	s_cmp_le_i32 s40, s34
	s_cbranch_scc1 .LBB0_1054
	v_add_u32_e32 v0, s14, v123
	v_cmp_lt_i32_e32 vcc, v0, v214
	v_add_u32_e32 v1, 2, v0
	s_nop 0
	v_cndmask_b32_e32 v81, v205, v81, vcc
	v_cmp_le_i32_e32 vcc, v0, v214
	s_nop 1
	v_cndmask_b32_e32 v80, v205, v80, vcc
	v_cmp_le_i32_e32 vcc, v1, v214
	v_add_u32_e32 v1, 3, v0
	s_nop 0
	v_cndmask_b32_e32 v2, v205, v2, vcc
	v_cmp_le_i32_e32 vcc, v1, v214
	v_add_u32_e32 v1, 8, v0
	s_nop 0
	v_cndmask_b32_e32 v3, v205, v3, vcc
	v_cmp_le_i32_e32 vcc, v1, v214
	v_add_u32_e32 v1, 9, v0
	s_nop 0
	v_cndmask_b32_e32 v4, v205, v4, vcc
	v_cmp_le_i32_e32 vcc, v1, v214
	v_add_u32_e32 v1, 10, v0
	s_nop 0
	v_cndmask_b32_e32 v5, v205, v5, vcc
	v_cmp_le_i32_e32 vcc, v1, v214
	v_add_u32_e32 v1, 11, v0
	s_nop 0
	v_cndmask_b32_e32 v6, v205, v6, vcc
	v_cmp_le_i32_e32 vcc, v1, v214
	v_add_u32_e32 v1, 16, v0
	s_nop 0
	v_cndmask_b32_e32 v7, v205, v7, vcc
	v_cmp_le_i32_e32 vcc, v1, v214
	v_add_u32_e32 v1, 17, v0
	s_nop 0
	v_cndmask_b32_e32 v8, v205, v8, vcc
	v_cmp_le_i32_e32 vcc, v1, v214
	v_add_u32_e32 v1, 18, v0
	s_nop 0
	v_cndmask_b32_e32 v9, v205, v9, vcc
	v_cmp_le_i32_e32 vcc, v1, v214
	v_add_u32_e32 v1, 19, v0
	s_nop 0
	v_cndmask_b32_e32 v10, v205, v10, vcc
	v_cmp_le_i32_e32 vcc, v1, v214
	v_add_u32_e32 v1, 24, v0
	s_nop 0
	v_cndmask_b32_e32 v11, v205, v11, vcc
	v_cmp_le_i32_e32 vcc, v1, v214
	v_add_u32_e32 v1, 25, v0
	s_nop 0
	v_cndmask_b32_e32 v12, v205, v12, vcc
	v_cmp_le_i32_e32 vcc, v1, v214
	v_add_u32_e32 v1, 26, v0
	v_add_u32_e32 v0, 27, v0
	v_cndmask_b32_e32 v13, v205, v13, vcc
	v_cmp_le_i32_e32 vcc, v1, v214
	s_nop 1
	v_cndmask_b32_e32 v14, v205, v14, vcc
	v_cmp_le_i32_e32 vcc, v0, v214
	s_nop 1
	v_cndmask_b32_e32 v15, v205, v15, vcc
.LBB0_1054:
	v_max_f32_e32 v0, v81, v81
	v_max_f32_e32 v1, v80, v80
	v_max_f32_e32 v0, v1, v0
	v_max3_f32 v0, v0, v2, v3
	v_max3_f32 v0, v0, v4, v5
	v_max3_f32 v0, v0, v6, v7
	v_max3_f32 v0, v0, v8, v9
	v_max3_f32 v0, v0, v10, v11
	v_max3_f32 v0, v0, v12, v13
	v_max3_f32 v0, v0, v14, v15
	v_mov_b32_e32 v1, v0
	s_nop 1
	v_permlane32_swap_b32_e32 v0, v1
	v_max3_f32 v212, v124, v0, v1
	v_add_f32_e32 v191, 0x41000000, v124
	v_cmp_gt_f32_e32 vcc, v212, v191
	s_cbranch_vccnz .Lmla_upd_1
	v_cmp_neq_f32_e32 vcc, s5, v124
	v_mov_b32_e32 v212, v124
	v_mov_b32_e32 v0, 1.0
	v_cndmask_b32_e32 v1, 0, v124, vcc
	s_branch .LBB0_1056

; #define LAS __attribute__((address_space(3)))
; DI int crow(int i, int h) { return (i & 3) + 8 * (i >> 2) + 4 * h; }
; #define MFMA32(a, b, c) __builtin_amdgcn_mfma_f32_32x32x16_bf16((a), (b), (c), 0, 0, 0)
; template <bool ATOM>
; DI void mla_unit(LAS unsigned char* lds, const AttnPtrs& P, int b, int hd, int qb) {
;     ...
;         if (keyb <= qb * 128 + rg * 32 + 31) {
;             const LAS unsigned char* Kw = lds + (t & 1) * BUFB + kwo;
;             const LAS unsigned char* Vw = lds + (t & 1) * BUFB + vwo;
;             f32x16 xa, xb;
; #pragma unroll
;             for (int i = 0; i < 16; ++i) { xa[i] = 0.f; xb[i] = 0.f; }
; #pragma unroll
;             for (int kk = 0; kk < NKK; kk += 2) {
;                 const bf16x8 a0 = *(const LAS bf16x8*)(Kw + kk * 32), a1 = *(const LAS bf16x8*)(Kw + kk * 32 + 32);
;                 xa = MFMA32(a0, qf[kk], xa); xb = MFMA32(a1, qf[kk + 1], xb);
;                 if ((kk & 3) == 2) __builtin_amdgcn_sched_barrier(0);
;             }
;             f32x16 x0;
; #pragma unroll
;             for (int i = 0; i < 16; ++i) x0[i] = xa[i] + xb[i];
;             if (keyb + 31 > qb * 128 + rg * 32) {
; #pragma unroll
;                 for (int i = 0; i < 16; ++i) if (keyb + crow(i, h) > fq_) x0[i] = -INFINITY;
;             }
.LBB0_1077:
	s_add_i32 s37, s23, s14
	s_cmp_gt_i32 s37, s34
	s_cbranch_scc1 .LBB0_1083
	s_bitcmp1_b32 s4, 0
	s_cselect_b32 s4, 0xac00, 0
	s_add_i32 s4, s4, 0
	v_add3_u32 v125, s4, v215, v128
	ds_read_b128 v[0:3], v125
	ds_read_b128 v[80:83], v125 offset:32
	ds_read_b128 v[216:219], v125 offset:64
	s_waitcnt lgkmcnt(2)
	v_mfma_f32_32x32x16_bf16 v[0:15], v[0:3], v[180:183], 0
	s_waitcnt lgkmcnt(0)
	v_mfma_f32_32x32x16_bf16 v[0:15], v[216:219], v[172:175], v[0:15]
	ds_read_b128 v[216:219], v125 offset:96
	v_mfma_f32_32x32x16_bf16 v[0:15], v[80:83], v[176:179], v[0:15]
	s_waitcnt lgkmcnt(0)
	v_mfma_f32_32x32x16_bf16 v[0:15], v[216:219], v[168:171], v[0:15]
	ds_read_b128 v[216:219], v125 offset:128
	s_waitcnt lgkmcnt(0)
	v_mfma_f32_32x32x16_bf16 v[0:15], v[216:219], v[164:167], v[0:15]
	ds_read_b128 v[216:219], v125 offset:160
	s_waitcnt lgkmcnt(0)
	v_mfma_f32_32x32x16_bf16 v[0:15], v[216:219], v[160:163], v[0:15]
	ds_read_b128 v[216:219], v125 offset:192
	s_waitcnt lgkmcnt(0)
	v_mfma_f32_32x32x16_bf16 v[0:15], v[216:219], v[156:159], v[0:15]
	ds_read_b128 v[216:219], v125 offset:224
	s_waitcnt lgkmcnt(0)
	v_mfma_f32_32x32x16_bf16 v[0:15], v[216:219], v[152:155], v[0:15]
	ds_read_b128 v[216:219], v125 offset:256
	s_waitcnt lgkmcnt(0)
	v_mfma_f32_32x32x16_bf16 v[0:15], v[216:219], v[148:151], v[0:15]
	ds_read_b128 v[216:219], v125 offset:288
	s_waitcnt lgkmcnt(0)
	v_mfma_f32_32x32x16_bf16 v[0:15], v[216:219], v[144:147], v[0:15]
	ds_read_b128 v[216:219], v125 offset:320
	s_waitcnt lgkmcnt(0)
	v_mfma_f32_32x32x16_bf16 v[0:15], v[216:219], v[140:143], v[0:15]
	ds_read_b128 v[216:219], v125 offset:352
	s_waitcnt lgkmcnt(0)
	v_mfma_f32_32x32x16_bf16 v[0:15], v[216:219], v[136:139], v[0:15]
	s_add_i32 s37, s37, 31
	s_nop 10
	v_mov_b32_e32 v80, v0
	v_mov_b32_e32 v81, v1
	s_cmp_le_i32 s37, s22
	s_cbranch_scc1 .LBB0_1080
	v_add_u32_e32 v0, s14, v123
	v_cmp_lt_i32_e32 vcc, v0, v214
	v_add_u32_e32 v1, 2, v0
	s_nop 0
	v_cndmask_b32_e32 v81, v205, v81, vcc
	v_cmp_le_i32_e32 vcc, v0, v214
	s_nop 1
	v_cndmask_b32_e32 v80, v205, v80, vcc
	v_cmp_le_i32_e32 vcc, v1, v214
	v_add_u32_e32 v1, 3, v0
	s_nop 0
	v_cndmask_b32_e32 v2, v205, v2, vcc
	v_cmp_le_i32_e32 vcc, v1, v214
	v_add_u32_e32 v1, 8, v0
	s_nop 0
	v_cndmask_b32_e32 v3, v205, v3, vcc
	v_cmp_le_i32_e32 vcc, v1, v214
	v_add_u32_e32 v1, 9, v0
	s_nop 0
	v_cndmask_b32_e32 v4, v205, v4, vcc
	v_cmp_le_i32_e32 vcc, v1, v214
	v_add_u32_e32 v1, 10, v0
	s_nop 0
	v_cndmask_b32_e32 v5, v205, v5, vcc
	v_cmp_le_i32_e32 vcc, v1, v214
	v_add_u32_e32 v1, 11, v0
	s_nop 0
	v_cndmask_b32_e32 v6, v205, v6, vcc
	v_cmp_le_i32_e32 vcc, v1, v214
	v_add_u32_e32 v1, 16, v0
	s_nop 0
	v_cndmask_b32_e32 v7, v205, v7, vcc
	v_cmp_le_i32_e32 vcc, v1, v214
	v_add_u32_e32 v1, 17, v0
	s_nop 0
	v_cndmask_b32_e32 v8, v205, v8, vcc
	v_cmp_le_i32_e32 vcc, v1, v214
	v_add_u32_e32 v1, 18, v0
	s_nop 0
	v_cndmask_b32_e32 v9, v205, v9, vcc
	v_cmp_le_i32_e32 vcc, v1, v214
	v_add_u32_e32 v1, 19, v0
	s_nop 0
	v_cndmask_b32_e32 v10, v205, v10, vcc
	v_cmp_le_i32_e32 vcc, v1, v214
	v_add_u32_e32 v1, 24, v0
	s_nop 0
	v_cndmask_b32_e32 v11, v205, v11, vcc
	v_cmp_le_i32_e32 vcc, v1, v214
	v_add_u32_e32 v1, 25, v0
	s_nop 0
	v_cndmask_b32_e32 v12, v205, v12, vcc
	v_cmp_le_i32_e32 vcc, v1, v214
	v_add_u32_e32 v1, 26, v0
	v_add_u32_e32 v0, 27, v0
	v_cndmask_b32_e32 v13, v205, v13, vcc
	v_cmp_le_i32_e32 vcc, v1, v214
	s_nop 1
	v_cndmask_b32_e32 v14, v205, v14, vcc
	v_cmp_le_i32_e32 vcc, v0, v214
	s_nop 1
	v_cndmask_b32_e32 v15, v205, v15, vcc
